# attention tile: PV in c-major order (V frags re-read) so exp/cvt fillers spread to <=7 cost units per MFMA gap (cost-weighted VALU spacing, 3 exp max per gap)
# speedup vs baseline: 1.0116x; 1.0116x over previous
.LBB0_40:
	s_add_i32 s60, s59, 0
	v_add_u32_e32 v144, s60, v196
	ds_read_b128 v[188:191], v144
	ds_read_b128 v[200:203], v197
	v_xad_u32 v144, v196, 32, s60
	ds_read_b128 v[204:207], v144
	v_xor_b32_e32 v199, 32, v197
	ds_read_b128 v[216:219], v199
	v_xad_u32 v144, v196, 64, s60
	ds_read_b128 v[220:223], v144
	v_xor_b32_e32 v199, 64, v197
	ds_read_b128 v[224:227], v199
	s_waitcnt lgkmcnt(4)
	v_mfma_f32_32x32x16_bf16 v[128:143], v[188:191], v[200:203], 0
	v_xor_b32_e32 v144, 0x60, v196
	v_add_u32_e32 v144, s60, v144
	ds_read_b128 v[188:191], v144
	v_xor_b32_e32 v199, 0x60, v197
	ds_read_b128 v[200:203], v199
	s_waitcnt lgkmcnt(4)
	v_mfma_f32_32x32x16_bf16 v[128:143], v[204:207], v[216:219], v[128:143]
	v_xor_b32_e32 v144, 0x80, v196
	v_add_u32_e32 v144, s60, v144
	ds_read_b128 v[204:207], v144
	v_xor_b32_e32 v199, 0x80, v197
	ds_read_b128 v[216:219], v199
	s_waitcnt lgkmcnt(4)
	v_mfma_f32_32x32x16_bf16 v[128:143], v[220:223], v[224:227], v[128:143]
	v_xor_b32_e32 v144, 0xa0, v196
	v_add_u32_e32 v144, s60, v144
	ds_read_b128 v[220:223], v144
	v_xor_b32_e32 v199, 0xa0, v197
	ds_read_b128 v[224:227], v199
	s_waitcnt lgkmcnt(4)
	v_mfma_f32_32x32x16_bf16 v[128:143], v[188:191], v[200:203], v[128:143]
	v_xor_b32_e32 v144, 0xc0, v196
	v_add_u32_e32 v144, s60, v144
	ds_read_b128 v[188:191], v144
	v_xor_b32_e32 v199, 0xc0, v197
	ds_read_b128 v[200:203], v199
	s_waitcnt lgkmcnt(4)
	v_mfma_f32_32x32x16_bf16 v[156:171], v[204:207], v[216:219], 0
	v_xor_b32_e32 v144, 0xe0, v196
	v_add_u32_e32 v144, s60, v144
	ds_read_b128 v[204:207], v144
	v_xor_b32_e32 v199, 0xe0, v197
	ds_read_b128 v[216:219], v199
	s_waitcnt lgkmcnt(4)
	v_mfma_f32_32x32x16_bf16 v[156:171], v[220:223], v[224:227], v[156:171]
	v_add_u32_e32 v144, s60, v196
	ds_read_b128 v[220:223], v144 offset:8192
	ds_read_b128 v[224:227], v197
	v_exp_f32_e32 v128, v128
	v_exp_f32_e32 v129, v129
	v_exp_f32_e32 v130, v130
	s_waitcnt lgkmcnt(4)
	v_mfma_f32_32x32x16_bf16 v[156:171], v[188:191], v[200:203], v[156:171]
	v_xad_u32 v144, v196, 32, s60
	ds_read_b128 v[188:191], v144 offset:8192
	v_xor_b32_e32 v199, 32, v197
	ds_read_b128 v[200:203], v199
	v_exp_f32_e32 v131, v131
	v_exp_f32_e32 v132, v132
	v_exp_f32_e32 v133, v133
	s_waitcnt lgkmcnt(4)
	v_mfma_f32_32x32x16_bf16 v[156:171], v[204:207], v[216:219], v[156:171]
	v_xad_u32 v144, v196, 64, s60
	ds_read_b128 v[204:207], v144 offset:8192
	v_xor_b32_e32 v199, 64, v197
	ds_read_b128 v[216:219], v199
	v_exp_f32_e32 v134, v134
	v_exp_f32_e32 v135, v135
	v_exp_f32_e32 v136, v136
	s_waitcnt lgkmcnt(4)
	v_mfma_f32_32x32x16_bf16 v[172:187], v[220:223], v[224:227], 0
	v_xor_b32_e32 v144, 0x60, v196
	v_add_u32_e32 v144, s60, v144
	ds_read_b128 v[220:223], v144 offset:8192
	v_xor_b32_e32 v199, 0x60, v197
	ds_read_b128 v[224:227], v199
	v_exp_f32_e32 v137, v137
	v_exp_f32_e32 v138, v138
	v_exp_f32_e32 v139, v139
	s_waitcnt lgkmcnt(4)
	v_mfma_f32_32x32x16_bf16 v[172:187], v[188:191], v[200:203], v[172:187]
	v_xor_b32_e32 v144, 0x80, v196
	v_add_u32_e32 v144, s60, v144
	ds_read_b128 v[188:191], v144 offset:8192
	v_xor_b32_e32 v199, 0x80, v197
	ds_read_b128 v[200:203], v199
	v_exp_f32_e32 v140, v140
	v_exp_f32_e32 v141, v141
	v_exp_f32_e32 v142, v142
	s_waitcnt lgkmcnt(4)
	v_mfma_f32_32x32x16_bf16 v[172:187], v[204:207], v[216:219], v[172:187]
	v_xor_b32_e32 v144, 0xa0, v196
	v_add_u32_e32 v144, s60, v144
	ds_read_b128 v[204:207], v144 offset:8192
	v_xor_b32_e32 v199, 0xa0, v197
	ds_read_b128 v[216:219], v199
	v_exp_f32_e32 v143, v143
	v_add_f32_e32 v192, v128, v129
	v_add_f32_e32 v193, v130, v131
	v_add_f32_e32 v192, v192, v132
	v_add_f32_e32 v193, v193, v133
	v_add_f32_e32 v192, v192, v134
	s_waitcnt lgkmcnt(4)
	v_mfma_f32_32x32x16_bf16 v[172:187], v[220:223], v[224:227], v[172:187]
	v_xor_b32_e32 v144, 0xc0, v196
	v_add_u32_e32 v144, s60, v144
	ds_read_b128 v[220:223], v144 offset:8192
	v_xor_b32_e32 v199, 0xc0, v197
	ds_read_b128 v[224:227], v199
	v_add_f32_e32 v193, v193, v135
	v_add_f32_e32 v192, v192, v136
	v_add_f32_e32 v193, v193, v137
	v_add_f32_e32 v192, v192, v138
	v_add_f32_e32 v193, v193, v139
	v_add_f32_e32 v192, v192, v140
	v_add_f32_e32 v193, v193, v141
	s_waitcnt lgkmcnt(4)
	v_mfma_f32_32x32x16_bf16 v[228:243], v[188:191], v[200:203], 0
	v_xor_b32_e32 v144, 0xe0, v196
	v_add_u32_e32 v144, s60, v144
	ds_read_b128 v[188:191], v144 offset:8192
	v_xor_b32_e32 v199, 0xe0, v197
	ds_read_b128 v[200:203], v199
	v_add_f32_e32 v192, v192, v142
	v_add_f32_e32 v193, v193, v143
	v_add_f32_e32 v192, v192, v193
	v_add_f32_e32 v150, v150, v192
	v_cvt_pk_bf16_f32 v128, v128, v129
	v_cvt_pk_bf16_f32 v129, v130, v131
	v_cvt_pk_bf16_f32 v130, v132, v133
	s_waitcnt lgkmcnt(4)
	v_mfma_f32_32x32x16_bf16 v[228:243], v[204:207], v[216:219], v[228:243]
	v_add_u32_e32 v248, s60, v198
	v_xad_u32 v249, v198, 32, s60
	ds_read_b128 v[204:207], v248
	ds_read_b128 v[216:219], v249
	v_cvt_pk_bf16_f32 v131, v134, v135
	v_cvt_pk_bf16_f32 v132, v136, v137
	v_cvt_pk_bf16_f32 v133, v138, v139
	v_cvt_pk_bf16_f32 v134, v140, v141
	v_cvt_pk_bf16_f32 v135, v142, v143
	v_exp_f32_e32 v156, v156
	s_waitcnt lgkmcnt(4)
	v_mfma_f32_32x32x16_bf16 v[228:243], v[220:223], v[224:227], v[228:243]
	ds_read_b128 v[220:223], v248 offset:4096
	ds_read_b128 v[224:227], v249 offset:4096
	v_exp_f32_e32 v157, v157
	v_exp_f32_e32 v158, v158
	v_exp_f32_e32 v159, v159
	s_waitcnt lgkmcnt(4)
	v_mfma_f32_32x32x16_bf16 v[228:243], v[188:191], v[200:203], v[228:243]
	ds_read_b128 v[188:191], v248 offset:8192
	ds_read_b128 v[200:203], v249 offset:8192
	v_exp_f32_e32 v160, v160
	v_exp_f32_e32 v161, v161
	v_exp_f32_e32 v162, v162
	s_waitcnt lgkmcnt(4)
	v_mfma_f32_32x32x16_bf16 v[112:127], v[204:207], v[128:131], v[112:127]
	v_exp_f32_e32 v163, v163
	v_exp_f32_e32 v164, v164
	v_exp_f32_e32 v165, v165
	v_mfma_f32_32x32x16_bf16 v[112:127], v[216:219], v[132:135], v[112:127]
	ds_read_b128 v[204:207], v248 offset:12288
	ds_read_b128 v[216:219], v249 offset:12288
	v_exp_f32_e32 v166, v166
	v_exp_f32_e32 v167, v167
	v_exp_f32_e32 v168, v168
	s_waitcnt lgkmcnt(4)
	v_mfma_f32_32x32x16_bf16 v[80:95], v[220:223], v[128:131], v[80:95]
	v_exp_f32_e32 v169, v169
	v_exp_f32_e32 v170, v170
	v_exp_f32_e32 v171, v171
	v_add_f32_e32 v192, v156, v157
	v_mfma_f32_32x32x16_bf16 v[80:95], v[224:227], v[132:135], v[80:95]
	ds_read_b128 v[220:223], v248
	ds_read_b128 v[224:227], v249
	v_add_f32_e32 v193, v158, v159
	v_add_f32_e32 v192, v192, v160
	v_add_f32_e32 v193, v193, v161
	v_add_f32_e32 v192, v192, v162
	v_add_f32_e32 v193, v193, v163
	v_add_f32_e32 v192, v192, v164
	v_add_f32_e32 v193, v193, v165
	s_waitcnt lgkmcnt(4)
	v_mfma_f32_32x32x16_bf16 v[48:63], v[188:191], v[128:131], v[48:63]
	v_add_f32_e32 v192, v192, v166
	v_add_f32_e32 v193, v193, v167
	v_add_f32_e32 v192, v192, v168
	v_add_f32_e32 v193, v193, v169
	v_add_f32_e32 v192, v192, v170
	v_add_f32_e32 v193, v193, v171
	v_add_f32_e32 v192, v192, v193
	v_mfma_f32_32x32x16_bf16 v[48:63], v[200:203], v[132:135], v[48:63]
	ds_read_b128 v[188:191], v248 offset:4096
	ds_read_b128 v[200:203], v249 offset:4096
	v_add_f32_e32 v151, v151, v192
	v_cvt_pk_bf16_f32 v156, v156, v157
	v_cvt_pk_bf16_f32 v157, v158, v159
	v_cvt_pk_bf16_f32 v158, v160, v161
	v_cvt_pk_bf16_f32 v159, v162, v163
	v_cvt_pk_bf16_f32 v160, v164, v165
	v_cvt_pk_bf16_f32 v161, v166, v167
	s_waitcnt lgkmcnt(4)
	v_mfma_f32_32x32x16_bf16 v[16:31], v[204:207], v[128:131], v[16:31]
	v_cvt_pk_bf16_f32 v162, v168, v169
	v_cvt_pk_bf16_f32 v163, v170, v171
	v_exp_f32_e32 v172, v172
	v_exp_f32_e32 v173, v173
	v_mfma_f32_32x32x16_bf16 v[16:31], v[216:219], v[132:135], v[16:31]
	ds_read_b128 v[204:207], v248 offset:8192
	ds_read_b128 v[216:219], v249 offset:8192
	v_exp_f32_e32 v174, v174
	v_exp_f32_e32 v175, v175
	v_exp_f32_e32 v176, v176
	s_waitcnt lgkmcnt(4)
	v_mfma_f32_32x32x16_bf16 v[96:111], v[220:223], v[156:159], v[96:111]
	v_exp_f32_e32 v177, v177
	v_exp_f32_e32 v178, v178
	v_exp_f32_e32 v179, v179
	v_mfma_f32_32x32x16_bf16 v[96:111], v[224:227], v[160:163], v[96:111]
	ds_read_b128 v[220:223], v248 offset:12288
	ds_read_b128 v[224:227], v249 offset:12288
	v_exp_f32_e32 v180, v180
	v_exp_f32_e32 v181, v181
	v_exp_f32_e32 v182, v182
	s_waitcnt lgkmcnt(4)
	v_mfma_f32_32x32x16_bf16 v[64:79], v[188:191], v[156:159], v[64:79]
	v_exp_f32_e32 v183, v183
	v_exp_f32_e32 v184, v184
	v_exp_f32_e32 v185, v185
	v_mfma_f32_32x32x16_bf16 v[64:79], v[200:203], v[160:163], v[64:79]
	v_xad_u32 v248, v198, 64, s60
	v_xor_b32_e32 v249, 0x60, v198
	v_add_u32_e32 v249, s60, v249
	ds_read_b128 v[188:191], v248
	ds_read_b128 v[200:203], v249
	v_exp_f32_e32 v186, v186
	v_exp_f32_e32 v187, v187
	v_add_f32_e32 v192, v172, v173
	v_add_f32_e32 v193, v174, v175
	v_add_f32_e32 v192, v192, v176
	s_waitcnt lgkmcnt(4)
	v_mfma_f32_32x32x16_bf16 v[32:47], v[204:207], v[156:159], v[32:47]
	v_add_f32_e32 v193, v193, v177
	v_add_f32_e32 v192, v192, v178
	v_add_f32_e32 v193, v193, v179
	v_add_f32_e32 v192, v192, v180
	v_add_f32_e32 v193, v193, v181
	v_add_f32_e32 v192, v192, v182
	v_add_f32_e32 v193, v193, v183
	v_mfma_f32_32x32x16_bf16 v[32:47], v[216:219], v[160:163], v[32:47]
	ds_read_b128 v[204:207], v248 offset:4096
	ds_read_b128 v[216:219], v249 offset:4096
	v_add_f32_e32 v192, v192, v184
	v_add_f32_e32 v193, v193, v185
	v_add_f32_e32 v192, v192, v186
	v_add_f32_e32 v193, v193, v187
	v_add_f32_e32 v192, v192, v193
	v_add_f32_e32 v150, v150, v192
	v_cvt_pk_bf16_f32 v172, v172, v173
	s_waitcnt lgkmcnt(4)
	v_mfma_f32_32x32x16_bf16 v[0:15], v[220:223], v[156:159], v[0:15]
	v_cvt_pk_bf16_f32 v173, v174, v175
	v_cvt_pk_bf16_f32 v174, v176, v177
	v_cvt_pk_bf16_f32 v175, v178, v179
	v_cvt_pk_bf16_f32 v176, v180, v181
	v_cvt_pk_bf16_f32 v177, v182, v183
	v_cvt_pk_bf16_f32 v178, v184, v185
	v_cvt_pk_bf16_f32 v179, v186, v187
	v_mfma_f32_32x32x16_bf16 v[0:15], v[224:227], v[160:163], v[0:15]
	ds_read_b128 v[220:223], v248 offset:8192
	ds_read_b128 v[224:227], v249 offset:8192
	v_exp_f32_e32 v228, v228
	v_exp_f32_e32 v229, v229
	v_exp_f32_e32 v230, v230
	s_waitcnt lgkmcnt(4)
	v_mfma_f32_32x32x16_bf16 v[112:127], v[188:191], v[172:175], v[112:127]
	v_exp_f32_e32 v231, v231
	v_exp_f32_e32 v232, v232
	v_exp_f32_e32 v233, v233
	v_mfma_f32_32x32x16_bf16 v[112:127], v[200:203], v[176:179], v[112:127]
	ds_read_b128 v[188:191], v248 offset:12288
	ds_read_b128 v[200:203], v249 offset:12288
	v_exp_f32_e32 v234, v234
	v_exp_f32_e32 v235, v235
	v_exp_f32_e32 v236, v236
	s_waitcnt lgkmcnt(4)
	v_mfma_f32_32x32x16_bf16 v[80:95], v[204:207], v[172:175], v[80:95]
	v_exp_f32_e32 v237, v237
	v_exp_f32_e32 v238, v238
	v_exp_f32_e32 v239, v239
	v_mfma_f32_32x32x16_bf16 v[80:95], v[216:219], v[176:179], v[80:95]
	ds_read_b128 v[204:207], v248
	ds_read_b128 v[216:219], v249
	v_exp_f32_e32 v240, v240
	v_exp_f32_e32 v241, v241
	v_exp_f32_e32 v242, v242
	s_waitcnt lgkmcnt(4)
	v_mfma_f32_32x32x16_bf16 v[48:63], v[220:223], v[172:175], v[48:63]
	v_exp_f32_e32 v243, v243
	v_add_f32_e32 v192, v228, v229
	v_add_f32_e32 v193, v230, v231
	v_add_f32_e32 v192, v192, v232
	v_add_f32_e32 v193, v193, v233
	v_add_f32_e32 v192, v192, v234
	v_mfma_f32_32x32x16_bf16 v[48:63], v[224:227], v[176:179], v[48:63]
	ds_read_b128 v[220:223], v248 offset:4096
	ds_read_b128 v[224:227], v249 offset:4096
	v_add_f32_e32 v193, v193, v235
	v_add_f32_e32 v192, v192, v236
	v_add_f32_e32 v193, v193, v237
	v_add_f32_e32 v192, v192, v238
	v_add_f32_e32 v193, v193, v239
	v_add_f32_e32 v192, v192, v240
	v_add_f32_e32 v193, v193, v241
	s_waitcnt lgkmcnt(4)
	v_mfma_f32_32x32x16_bf16 v[16:31], v[188:191], v[172:175], v[16:31]
	v_add_f32_e32 v192, v192, v242
	v_add_f32_e32 v193, v193, v243
	v_add_f32_e32 v192, v192, v193
	v_add_f32_e32 v151, v151, v192
	v_cvt_pk_bf16_f32 v228, v228, v229
	v_cvt_pk_bf16_f32 v229, v230, v231
	v_cvt_pk_bf16_f32 v230, v232, v233
	v_mfma_f32_32x32x16_bf16 v[16:31], v[200:203], v[176:179], v[16:31]
	ds_read_b128 v[188:191], v248 offset:8192
	ds_read_b128 v[200:203], v249 offset:8192
	v_cvt_pk_bf16_f32 v231, v234, v235
	v_cvt_pk_bf16_f32 v232, v236, v237
	v_cvt_pk_bf16_f32 v233, v238, v239
	v_cvt_pk_bf16_f32 v234, v240, v241
	v_cvt_pk_bf16_f32 v235, v242, v243
	s_waitcnt lgkmcnt(4)
	v_mfma_f32_32x32x16_bf16 v[96:111], v[204:207], v[228:231], v[96:111]
	v_mfma_f32_32x32x16_bf16 v[96:111], v[216:219], v[232:235], v[96:111]
	ds_read_b128 v[204:207], v248 offset:12288
	ds_read_b128 v[216:219], v249 offset:12288
	s_waitcnt lgkmcnt(4)
	v_mfma_f32_32x32x16_bf16 v[64:79], v[220:223], v[228:231], v[64:79]
	v_mfma_f32_32x32x16_bf16 v[64:79], v[224:227], v[232:235], v[64:79]
	s_waitcnt lgkmcnt(2)
	v_mfma_f32_32x32x16_bf16 v[32:47], v[188:191], v[228:231], v[32:47]
	v_mfma_f32_32x32x16_bf16 v[32:47], v[200:203], v[232:235], v[32:47]
	s_waitcnt lgkmcnt(0)
	v_mfma_f32_32x32x16_bf16 v[0:15], v[204:207], v[228:231], v[0:15]
	v_mfma_f32_32x32x16_bf16 v[0:15], v[216:219], v[232:235], v[0:15]
	s_mov_b64 s[92:93], -1
	s_and_b64 vcc, exec, s[86:87]
	s_cbranch_vccnz .LBB0_38
